# attention: raise priority of waves active on a tile over co-resident inactive waves (s_setprio per qkt site); stacked on gMLP rewrite + qkt/pv read pipelining
# baseline (speedup 1.0000x reference)
; #define SBAR() __builtin_amdgcn_sched_barrier(0)
; #define ACT(t) (KBASE(t) <= qlo + QBLK - 1 && KBASE(t) + KVBLK - 1 >= qlo - W + 1)
; template <int KB, bool SK>
; __device__ __forceinline__ void qkt(f32x16& p0, f32x16& p1, const char* K_lds, int r32, int hi, const bf16x8* qr, bool act) {
;     if (SK && !act) { const float NEG = -__builtin_inff();
; #pragma unroll
;         for (int r = 0; r < 16; ++r) { p0[r] = NEG; p1[r] = NEG; } return; }
;     p0 = f32x16{}; p1 = f32x16{};
;     const char* kb[4];
; #pragma unroll
;     for (int dd = 0; dd < 4; ++dd) kb[dd] = K_lds + KB * SHM_K + KSWZ(r32, (dd * 16 + hi * 8) * 2);
; #pragma unroll
;     for (int d0 = 0; d0 < 8; ++d0) { const char* a = kb[d0 & 3] + (d0 >> 2) * 128;
;         bf16x8 b0 = *reinterpret_cast<const bf16x8*>(a);
;         bf16x8 b1 = *reinterpret_cast<const bf16x8*>(a + 32 * 256);
;         p0 = __builtin_amdgcn_mfma_f32_32x32x16_bf16(b0, qr[d0], p0, 0, 0, 0);
;         p1 = __builtin_amdgcn_mfma_f32_32x32x16_bf16(b1, qr[d0], p1, 0, 0, 0); }
; }
; template <class TIn, class TOut>
; __device__ __forceinline__ void causal_swa_block(const BlockRef<TIn, TOut>& cur, const BlockRef<TIn, TOut>& nxt, int skv, int W, char* lds, Seam<TIn>& S) {
;     ...
;     SBAR(); qkt<0, SK>(pA0, pA1, K_lds, r32, hi, S.qr, ACT(0));
.LBB0_229:
	s_ashr_i32 s52, s10, 1
	s_andn2_b32 s52, s52, 31
	v_and_b32_e32 v210, 31, v209
	v_bfe_u32 v34, v209, 5, 1
	s_add_i32 s54, s52, s45
	s_add_i32 s55, s54, 31
	s_cmp_gt_i32 s60, s55
	s_cselect_b64 s[6:7], -1, 0
	s_or_b32 s11, s60, 63
	s_add_i32 s56, s54, 0xffffff80
	s_cmp_lt_i32 s11, s56
	s_cselect_b64 s[38:39], -1, 0
	s_or_b64 s[6:7], s[6:7], s[38:39]
	s_and_b64 vcc, exec, s[6:7]
	v_lshlrev_b32_e32 v202, 4, v34
	s_cbranch_vccnz .LBB0_231
	s_setprio 1
	v_lshlrev_b32_e32 v6, 4, v210
	s_movk_i32 s38, 0x70
	v_lshlrev_b32_e32 v1, 8, v210
	v_bitop3_b32 v2, v202, v6, s38 bitop3:0x78
	v_add3_u32 v35, 0, v2, v1
	ds_read_b128 v[2:5], v35 offset:32768
	v_and_b32_e32 v40, 0x70, v6
	v_bitop3_b32 v6, v202, v40, 32 bitop3:0x36
	v_add3_u32 v41, 0, v6, v1
	ds_read_b128 v[36:39], v41 offset:32768
	v_bitop3_b32 v42, v202, v40, 64 bitop3:0x36
	v_add3_u32 v42, 0, v42, v1
	s_waitcnt vmcnt(7) lgkmcnt(1)
	v_mfma_f32_32x32x16_bf16 v[18:33], v[2:5], v[172:175], 0
	ds_read_b128 v[2:5], v35 offset:40960
	s_movk_i32 s38, 0x60
	v_bitop3_b32 v40, v202, v40, s38 bitop3:0x36
	v_add3_u32 v1, 0, v40, v1
	s_waitcnt vmcnt(6) lgkmcnt(1)
	v_mfma_f32_32x32x16_bf16 v[18:33], v[36:39], v[168:171], v[18:33]
	ds_read_b128 v[36:39], v41 offset:40960
	s_waitcnt lgkmcnt(1)
	v_mfma_f32_32x32x16_bf16 v[2:17], v[2:5], v[172:175], 0
	s_waitcnt lgkmcnt(0)
	v_mfma_f32_32x32x16_bf16 v[2:17], v[36:39], v[168:171], v[2:17]
	ds_read_b128 v[36:39], v42 offset:32768
	s_waitcnt vmcnt(5) lgkmcnt(0)
	v_mfma_f32_32x32x16_bf16 v[18:33], v[36:39], v[164:167], v[18:33]
	ds_read_b128 v[36:39], v42 offset:40960
	s_waitcnt lgkmcnt(0)
	v_mfma_f32_32x32x16_bf16 v[2:17], v[36:39], v[164:167], v[2:17]
	ds_read_b128 v[36:39], v1 offset:32768
	s_waitcnt vmcnt(4) lgkmcnt(0)
	v_mfma_f32_32x32x16_bf16 v[18:33], v[36:39], v[160:163], v[18:33]
	ds_read_b128 v[36:39], v1 offset:40960
	s_waitcnt lgkmcnt(0)
	v_mfma_f32_32x32x16_bf16 v[2:17], v[36:39], v[160:163], v[2:17]
	ds_read_b128 v[36:39], v35 offset:32896
	s_waitcnt vmcnt(3) lgkmcnt(0)
	v_mfma_f32_32x32x16_bf16 v[18:33], v[36:39], v[156:159], v[18:33]
	ds_read_b128 v[36:39], v35 offset:41088
	s_waitcnt lgkmcnt(0)
	v_mfma_f32_32x32x16_bf16 v[2:17], v[36:39], v[156:159], v[2:17]
	ds_read_b128 v[36:39], v41 offset:32896
	s_waitcnt vmcnt(2) lgkmcnt(0)
	v_mfma_f32_32x32x16_bf16 v[18:33], v[36:39], v[152:155], v[18:33]
	ds_read_b128 v[36:39], v41 offset:41088
	s_waitcnt lgkmcnt(0)
	v_mfma_f32_32x32x16_bf16 v[2:17], v[36:39], v[152:155], v[2:17]
	ds_read_b128 v[36:39], v42 offset:32896
	s_waitcnt vmcnt(1) lgkmcnt(0)
	v_mfma_f32_32x32x16_bf16 v[18:33], v[36:39], v[148:151], v[18:33]
	ds_read_b128 v[36:39], v42 offset:41088
	s_waitcnt lgkmcnt(0)
	v_mfma_f32_32x32x16_bf16 v[2:17], v[36:39], v[148:151], v[2:17]
	ds_read_b128 v[36:39], v1 offset:32896
	s_waitcnt vmcnt(0) lgkmcnt(0)
	v_mfma_f32_32x32x16_bf16 v[18:33], v[36:39], v[144:147], v[18:33]
	ds_read_b128 v[36:39], v1 offset:41088
	s_waitcnt lgkmcnt(0)
	v_mfma_f32_32x32x16_bf16 v[2:17], v[36:39], v[144:147], v[2:17]
	s_branch .LBB0_232
.LBB0_231:
	s_setprio 0
	v_mov_b32_e32 v14, v0
	v_mov_b32_e32 v15, v0
	v_mov_b32_e32 v1, v0
	v_mov_b32_e32 v2, v0
	v_mov_b32_e32 v3, v0
	v_mov_b32_e32 v4, v0
	v_mov_b32_e32 v5, v0
	v_mov_b32_e32 v6, v0
	v_mov_b32_e32 v7, v0
	v_mov_b32_e32 v8, v0
	v_mov_b32_e32 v9, v0
	v_mov_b32_e32 v10, v0
	v_mov_b32_e32 v11, v0
	v_mov_b32_e32 v12, v0
	v_mov_b32_e32 v13, v0
	v_mov_b64_e32 v[32:33], v[14:15]
	v_mov_b64_e32 v[30:31], v[12:13]
	v_mov_b64_e32 v[28:29], v[10:11]
	v_mov_b64_e32 v[26:27], v[8:9]
	v_mov_b64_e32 v[24:25], v[6:7]
	v_mov_b64_e32 v[22:23], v[4:5]
	v_mov_b64_e32 v[20:21], v[2:3]
	v_mov_b64_e32 v[18:19], v[0:1]
	v_mov_b64_e32 v[16:17], v[14:15]
	v_mov_b64_e32 v[14:15], v[12:13]
	v_mov_b64_e32 v[12:13], v[10:11]
	v_mov_b64_e32 v[10:11], v[8:9]
	v_mov_b64_e32 v[8:9], v[6:7]
	v_mov_b64_e32 v[6:7], v[4:5]
	v_mov_b64_e32 v[4:5], v[2:3]
	v_mov_b64_e32 v[2:3], v[0:1]

; template <int KB, bool SK>
; __device__ __forceinline__ void qkt(f32x16& p0, f32x16& p1, const char* K_lds, int r32, int hi, const bf16x8* qr, bool act) {
;     if (SK && !act) { const float NEG = -__builtin_inff();
; #pragma unroll
;         for (int r = 0; r < 16; ++r) { p0[r] = NEG; p1[r] = NEG; } return; }
;     p0 = f32x16{}; p1 = f32x16{};
;     const char* kb[4];
; #pragma unroll
;     for (int dd = 0; dd < 4; ++dd) kb[dd] = K_lds + KB * SHM_K + KSWZ(r32, (dd * 16 + hi * 8) * 2);
; #pragma unroll
;     for (int d0 = 0; d0 < 8; ++d0) { const char* a = kb[d0 & 3] + (d0 >> 2) * 128;
;         bf16x8 b0 = *reinterpret_cast<const bf16x8*>(a);
;         bf16x8 b1 = *reinterpret_cast<const bf16x8*>(a + 32 * 256);
;         p0 = __builtin_amdgcn_mfma_f32_32x32x16_bf16(b0, qr[d0], p0, 0, 0, 0);
;         p1 = __builtin_amdgcn_mfma_f32_32x32x16_bf16(b1, qr[d0], p1, 0, 0, 0); }
; }
.LBB0_239:
	s_add_i32 s10, s60, 64
	s_cmp_gt_i32 s10, s55
	s_cselect_b64 s[8:9], -1, 0
	s_add_i32 s11, s60, 0x7f
	s_cmp_lt_i32 s11, s56
	s_cselect_b64 s[38:39], -1, 0
	s_or_b64 s[8:9], s[8:9], s[38:39]
	s_and_b64 vcc, exec, s[8:9]
	s_cbranch_vccnz .LBB0_241
	s_setprio 1
	s_waitcnt vmcnt(0)
	ds_read_b128 v[2:5], v228 offset:49152
	ds_read_b128 v[6:9], v228 offset:57344
	ds_read_b128 v[10:13], v229 offset:49152
	ds_read_b128 v[198:201], v229 offset:57344
	s_waitcnt lgkmcnt(3)
	v_mfma_f32_32x32x16_bf16 v[100:115], v[2:5], v[172:175], 0
	ds_read_b128 v[2:5], v230 offset:49152
	s_waitcnt lgkmcnt(3)
	v_mfma_f32_32x32x16_bf16 v[84:99], v[6:9], v[172:175], 0
	ds_read_b128 v[6:9], v230 offset:57344
	s_waitcnt lgkmcnt(3)
	v_mfma_f32_32x32x16_bf16 v[100:115], v[10:13], v[168:171], v[100:115]
	ds_read_b128 v[10:13], v231 offset:49152
	s_waitcnt lgkmcnt(3)
	v_mfma_f32_32x32x16_bf16 v[84:99], v[198:201], v[168:171], v[84:99]
	ds_read_b128 v[198:201], v231 offset:57344
	s_waitcnt lgkmcnt(3)
	v_mfma_f32_32x32x16_bf16 v[100:115], v[2:5], v[164:167], v[100:115]
	ds_read_b128 v[2:5], v228 offset:49280
	s_waitcnt lgkmcnt(3)
	v_mfma_f32_32x32x16_bf16 v[84:99], v[6:9], v[164:167], v[84:99]
	ds_read_b128 v[6:9], v228 offset:57472
	s_waitcnt lgkmcnt(3)
	v_mfma_f32_32x32x16_bf16 v[100:115], v[10:13], v[160:163], v[100:115]
	ds_read_b128 v[10:13], v229 offset:49280
	s_waitcnt lgkmcnt(3)
	v_mfma_f32_32x32x16_bf16 v[84:99], v[198:201], v[160:163], v[84:99]
	ds_read_b128 v[198:201], v229 offset:57472
	s_waitcnt lgkmcnt(3)
	v_mfma_f32_32x32x16_bf16 v[100:115], v[2:5], v[156:159], v[100:115]
	ds_read_b128 v[2:5], v230 offset:49280
	s_waitcnt lgkmcnt(3)
	v_mfma_f32_32x32x16_bf16 v[84:99], v[6:9], v[156:159], v[84:99]
	ds_read_b128 v[6:9], v230 offset:57472
	s_waitcnt lgkmcnt(3)
	v_mfma_f32_32x32x16_bf16 v[100:115], v[10:13], v[152:155], v[100:115]
	ds_read_b128 v[10:13], v231 offset:49280
	s_waitcnt lgkmcnt(3)
	v_mfma_f32_32x32x16_bf16 v[84:99], v[198:201], v[152:155], v[84:99]
	ds_read_b128 v[198:201], v231 offset:57472
	s_waitcnt lgkmcnt(3)
	v_mfma_f32_32x32x16_bf16 v[100:115], v[2:5], v[148:151], v[100:115]
	s_waitcnt lgkmcnt(2)
	v_mfma_f32_32x32x16_bf16 v[84:99], v[6:9], v[148:151], v[84:99]
	s_waitcnt lgkmcnt(1)
	v_mfma_f32_32x32x16_bf16 v[100:115], v[10:13], v[144:147], v[100:115]
	s_waitcnt lgkmcnt(0)
	v_mfma_f32_32x32x16_bf16 v[84:99], v[198:201], v[144:147], v[84:99]
	s_branch .LBB0_242
.LBB0_241:
	s_setprio 0
	v_mov_b32_e32 v14, v0
	v_mov_b32_e32 v15, v0
	v_mov_b32_e32 v1, v0
	v_mov_b32_e32 v2, v0
	v_mov_b32_e32 v3, v0
	v_mov_b32_e32 v4, v0
	v_mov_b32_e32 v5, v0
	v_mov_b32_e32 v6, v0
	v_mov_b32_e32 v7, v0
	v_mov_b32_e32 v8, v0
	v_mov_b32_e32 v9, v0
	v_mov_b32_e32 v10, v0
	v_mov_b32_e32 v11, v0
	v_mov_b32_e32 v12, v0
	v_mov_b32_e32 v13, v0
	s_waitcnt vmcnt(3)
	v_mov_b64_e32 v[114:115], v[14:15]
	v_mov_b64_e32 v[98:99], v[14:15]
	v_mov_b64_e32 v[112:113], v[12:13]
	v_mov_b64_e32 v[110:111], v[10:11]
	v_mov_b64_e32 v[108:109], v[8:9]
	v_mov_b64_e32 v[106:107], v[6:7]
	v_mov_b64_e32 v[104:105], v[4:5]
	v_mov_b64_e32 v[102:103], v[2:3]
	v_mov_b64_e32 v[100:101], v[0:1]
	v_mov_b64_e32 v[96:97], v[12:13]
	v_mov_b64_e32 v[94:95], v[10:11]
	v_mov_b64_e32 v[92:93], v[8:9]
	v_mov_b64_e32 v[90:91], v[6:7]
	v_mov_b64_e32 v[88:89], v[4:5]
	v_mov_b64_e32 v[86:87], v[2:3]
	v_mov_b64_e32 v[84:85], v[0:1]

; __device__ __forceinline__ void partialSM(f32x16& p0, f32x16& p1, float& m_reg, float& mn, float& alpha) {
;     ...
;     const float mnL = -mn * C2;
;     for (int r = 0; r < 16; ++r) p0[r] = fmaf(p0[r], C2, mnL); for (int r = 0; r < 16; ++r) p1[r] = fmaf(p1[r], C2, mnL);
;     for (int r = 0; r < 16; ++r) p0[r] = __builtin_amdgcn_exp2f(p0[r]);
.LBB0_251:
	v_cndmask_b32_e64 v236, v1, v192, s[10:11]
	v_mul_f32_e32 v192, 0xbe0293ee, v236
	v_fmamk_f32 v1, v100, 0x3e0293ee, v192
	v_fmamk_f32 v2, v101, 0x3e0293ee, v192
	v_fmamk_f32 v3, v102, 0x3e0293ee, v192
	v_fmamk_f32 v4, v103, 0x3e0293ee, v192
	v_fmamk_f32 v5, v104, 0x3e0293ee, v192
	v_fmamk_f32 v6, v105, 0x3e0293ee, v192
	v_fmamk_f32 v7, v106, 0x3e0293ee, v192
	v_fmamk_f32 v8, v107, 0x3e0293ee, v192
	v_fmamk_f32 v9, v108, 0x3e0293ee, v192
	v_fmamk_f32 v10, v109, 0x3e0293ee, v192
	v_fmamk_f32 v11, v110, 0x3e0293ee, v192
	v_fmamk_f32 v12, v111, 0x3e0293ee, v192
	v_fmamk_f32 v13, v112, 0x3e0293ee, v192
	v_fmamk_f32 v14, v113, 0x3e0293ee, v192
	v_fmamk_f32 v15, v114, 0x3e0293ee, v192
	v_fmamk_f32 v112, v115, 0x3e0293ee, v192
	v_fmamk_f32 v100, v84, 0x3e0293ee, v192
	v_fmamk_f32 v101, v85, 0x3e0293ee, v192
	v_fmamk_f32 v102, v86, 0x3e0293ee, v192
	v_fmamk_f32 v103, v87, 0x3e0293ee, v192
	v_fmamk_f32 v104, v88, 0x3e0293ee, v192
	v_fmamk_f32 v105, v89, 0x3e0293ee, v192
	v_fmamk_f32 v106, v90, 0x3e0293ee, v192
	v_fmamk_f32 v107, v91, 0x3e0293ee, v192
	v_fmamk_f32 v108, v92, 0x3e0293ee, v192
	v_fmamk_f32 v109, v93, 0x3e0293ee, v192
	v_fmamk_f32 v110, v94, 0x3e0293ee, v192
	v_fmamk_f32 v111, v95, 0x3e0293ee, v192
	v_exp_f32_e32 v80, v1
	v_exp_f32_e32 v81, v2
	v_exp_f32_e32 v82, v3
	v_exp_f32_e32 v83, v4
	v_exp_f32_e32 v84, v5
	v_exp_f32_e32 v85, v6
	v_exp_f32_e32 v86, v7
	v_exp_f32_e32 v87, v8
	v_exp_f32_e32 v88, v9
	v_exp_f32_e32 v89, v10
	v_exp_f32_e32 v90, v11
	v_exp_f32_e32 v91, v12
	v_exp_f32_e32 v92, v13
	v_exp_f32_e32 v93, v14
	v_exp_f32_e32 v94, v15
	v_exp_f32_e32 v95, v112
	v_fmamk_f32 v193, v96, 0x3e0293ee, v192
	v_fmamk_f32 v194, v97, 0x3e0293ee, v192
	v_fmamk_f32 v195, v98, 0x3e0293ee, v192
	v_fmac_f32_e32 v192, 0x3e0293ee, v99
	s_add_i32 s61, s60, 0x80
	s_waitcnt lgkmcnt(0)
	s_barrier
	s_cmp_gt_i32 s61, s55
	s_cselect_b64 s[10:11], -1, 0
	s_addk_i32 s60, 0xbf
	s_cmp_lt_i32 s60, s56
	s_cselect_b64 s[38:39], -1, 0
	s_or_b64 s[10:11], s[10:11], s[38:39]
	s_and_b64 vcc, exec, s[10:11]
	s_cbranch_vccnz .LBB0_253
	s_setprio 1
	ds_read_b128 v[2:5], v228 offset:32768
	ds_read_b128 v[6:9], v228 offset:40960
	ds_read_b128 v[10:13], v229 offset:32768
	ds_read_b128 v[198:201], v229 offset:40960
	s_waitcnt lgkmcnt(3)
	v_mfma_f32_32x32x16_bf16 v[128:143], v[2:5], v[172:175], 0
	ds_read_b128 v[2:5], v230 offset:32768
	s_waitcnt lgkmcnt(3)
	v_mfma_f32_32x32x16_bf16 v[112:127], v[6:9], v[172:175], 0
	ds_read_b128 v[6:9], v230 offset:40960
	s_waitcnt lgkmcnt(3)
	v_mfma_f32_32x32x16_bf16 v[128:143], v[10:13], v[168:171], v[128:143]
	ds_read_b128 v[10:13], v231 offset:32768
	s_waitcnt lgkmcnt(3)
	v_mfma_f32_32x32x16_bf16 v[112:127], v[198:201], v[168:171], v[112:127]
	ds_read_b128 v[198:201], v231 offset:40960
	s_waitcnt lgkmcnt(3)
	v_mfma_f32_32x32x16_bf16 v[128:143], v[2:5], v[164:167], v[128:143]
	ds_read_b128 v[2:5], v228 offset:32896
	s_waitcnt lgkmcnt(3)
	v_mfma_f32_32x32x16_bf16 v[112:127], v[6:9], v[164:167], v[112:127]
	ds_read_b128 v[6:9], v228 offset:41088
	s_waitcnt lgkmcnt(3)
	v_mfma_f32_32x32x16_bf16 v[128:143], v[10:13], v[160:163], v[128:143]
	ds_read_b128 v[10:13], v229 offset:32896
	s_waitcnt lgkmcnt(3)
	v_mfma_f32_32x32x16_bf16 v[112:127], v[198:201], v[160:163], v[112:127]
	ds_read_b128 v[198:201], v229 offset:41088
	s_waitcnt lgkmcnt(3)
	v_mfma_f32_32x32x16_bf16 v[128:143], v[2:5], v[156:159], v[128:143]
	ds_read_b128 v[2:5], v230 offset:32896
	s_waitcnt lgkmcnt(3)
	v_mfma_f32_32x32x16_bf16 v[112:127], v[6:9], v[156:159], v[112:127]
	ds_read_b128 v[6:9], v230 offset:41088
	s_waitcnt lgkmcnt(3)
	v_mfma_f32_32x32x16_bf16 v[128:143], v[10:13], v[152:155], v[128:143]
	ds_read_b128 v[10:13], v231 offset:32896
	s_waitcnt lgkmcnt(3)
	v_mfma_f32_32x32x16_bf16 v[112:127], v[198:201], v[152:155], v[112:127]
	ds_read_b128 v[198:201], v231 offset:41088
	s_waitcnt lgkmcnt(3)
	v_mfma_f32_32x32x16_bf16 v[128:143], v[2:5], v[148:151], v[128:143]
	s_waitcnt lgkmcnt(2)
	v_mfma_f32_32x32x16_bf16 v[112:127], v[6:9], v[148:151], v[112:127]
	s_waitcnt lgkmcnt(1)
	v_mfma_f32_32x32x16_bf16 v[128:143], v[10:13], v[144:147], v[128:143]
	s_waitcnt lgkmcnt(0)
	v_mfma_f32_32x32x16_bf16 v[112:127], v[198:201], v[144:147], v[112:127]
	s_branch .LBB0_254
.LBB0_253:
	s_setprio 0
	v_mov_b32_e32 v14, v0
	v_mov_b32_e32 v15, v0
	v_mov_b32_e32 v1, v0
	v_mov_b32_e32 v2, v0
	v_mov_b32_e32 v3, v0
	v_mov_b32_e32 v4, v0
	v_mov_b32_e32 v5, v0
	v_mov_b32_e32 v6, v0
	v_mov_b32_e32 v7, v0
	v_mov_b32_e32 v8, v0
	v_mov_b32_e32 v9, v0
	v_mov_b32_e32 v10, v0
	v_mov_b32_e32 v11, v0
	v_mov_b32_e32 v12, v0
	v_mov_b32_e32 v13, v0
	v_mov_b64_e32 v[142:143], v[14:15]
	v_mov_b64_e32 v[126:127], v[14:15]
	v_mov_b64_e32 v[140:141], v[12:13]
	v_mov_b64_e32 v[138:139], v[10:11]
	v_mov_b64_e32 v[136:137], v[8:9]
	v_mov_b64_e32 v[134:135], v[6:7]
	v_mov_b64_e32 v[132:133], v[4:5]
	v_mov_b64_e32 v[130:131], v[2:3]
	v_mov_b64_e32 v[128:129], v[0:1]
	v_mov_b64_e32 v[124:125], v[12:13]
	v_mov_b64_e32 v[122:123], v[10:11]
	v_mov_b64_e32 v[120:121], v[8:9]
	v_mov_b64_e32 v[118:119], v[6:7]
	v_mov_b64_e32 v[116:117], v[4:5]
	v_mov_b64_e32 v[114:115], v[2:3]
	v_mov_b64_e32 v[112:113], v[0:1]

; #define SBAR() __builtin_amdgcn_sched_barrier(0)
; #define ACT(t) (KBASE(t) <= qlo + QBLK - 1 && KBASE(t) + KVBLK - 1 >= qlo - W + 1)
; template <int KB, bool SK>
; __device__ __forceinline__ void qkt(f32x16& p0, f32x16& p1, const char* K_lds, int r32, int hi, const bf16x8* qr, bool act) {
;     if (SK && !act) { const float NEG = -__builtin_inff();
; #pragma unroll
;         for (int r = 0; r < 16; ++r) { p0[r] = NEG; p1[r] = NEG; } return; }
;     p0 = f32x16{}; p1 = f32x16{};
;     const char* kb[4];
; #pragma unroll
;     for (int dd = 0; dd < 4; ++dd) kb[dd] = K_lds + KB * SHM_K + KSWZ(r32, (dd * 16 + hi * 8) * 2);
; #pragma unroll
;     for (int d0 = 0; d0 < 8; ++d0) { const char* a = kb[d0 & 3] + (d0 >> 2) * 128;
;         bf16x8 b0 = *reinterpret_cast<const bf16x8*>(a);
;         bf16x8 b1 = *reinterpret_cast<const bf16x8*>(a + 32 * 256);
;         p0 = __builtin_amdgcn_mfma_f32_32x32x16_bf16(b0, qr[d0], p0, 0, 0, 0);
;         p1 = __builtin_amdgcn_mfma_f32_32x32x16_bf16(b1, qr[d0], p1, 0, 0, 0); }
; }
; template <class TIn, class TOut>
; __device__ __forceinline__ void causal_swa_block(const BlockRef<TIn, TOut>& cur, const BlockRef<TIn, TOut>& nxt, int skv, int W, char* lds, Seam<TIn>& S) {
;     ...
;     if (even) { SBAR(); qkt<1, SK>(pB0, pB1, K_lds, r32, hi, S.qr, ACT(NT - 1)); SBAR(); }
.LBB0_271:
	s_lshl_b32 s10, s53, 6
	s_sub_i32 s8, s10, 64
	s_cmp_le_i32 s8, s55
	s_cselect_b64 s[8:9], -1, 0
	s_cmp_gt_i32 s10, s56
	s_cselect_b64 s[10:11], -1, 0
	s_and_b64 s[8:9], s[8:9], s[10:11]
	s_andn2_b64 vcc, exec, s[8:9]
	s_cbranch_vccnz .LBB0_273
	s_setprio 1
	v_lshlrev_b32_e32 v2, 4, v210
	s_movk_i32 s8, 0x70
	v_lshlrev_b32_e32 v1, 8, v210
	v_and_b32_e32 v3, 0x70, v2
	v_bitop3_b32 v2, v202, v2, s8 bitop3:0x78
	v_add3_u32 v10, 0, v2, v1
	v_bitop3_b32 v2, v202, v3, 32 bitop3:0x36
	v_add3_u32 v11, 0, v2, v1
	v_bitop3_b32 v2, v202, v3, 64 bitop3:0x36
	s_movk_i32 s8, 0x60
	v_add3_u32 v12, 0, v2, v1
	v_bitop3_b32 v2, v202, v3, s8 bitop3:0x36
	v_add3_u32 v1, 0, v2, v1
	ds_read_b128 v[2:5], v10 offset:49152
	ds_read_b128 v[6:9], v10 offset:57344
	s_waitcnt vmcnt(7) lgkmcnt(1)
	v_mfma_f32_32x32x16_bf16 v[80:95], v[2:5], v[172:175], 0
	s_waitcnt lgkmcnt(0)
	v_mfma_f32_32x32x16_bf16 v[96:111], v[6:9], v[172:175], 0
	ds_read_b128 v[2:5], v11 offset:49152
	ds_read_b128 v[6:9], v11 offset:57344
	s_waitcnt vmcnt(6) lgkmcnt(1)
	v_mfma_f32_32x32x16_bf16 v[80:95], v[2:5], v[168:171], v[80:95]
	s_waitcnt lgkmcnt(0)
	v_mfma_f32_32x32x16_bf16 v[96:111], v[6:9], v[168:171], v[96:111]
	ds_read_b128 v[2:5], v12 offset:49152
	ds_read_b128 v[6:9], v12 offset:57344
	s_waitcnt vmcnt(5) lgkmcnt(1)
	v_mfma_f32_32x32x16_bf16 v[80:95], v[2:5], v[164:167], v[80:95]
	s_waitcnt lgkmcnt(0)
	v_mfma_f32_32x32x16_bf16 v[96:111], v[6:9], v[164:167], v[96:111]
	ds_read_b128 v[2:5], v1 offset:49152
	ds_read_b128 v[6:9], v1 offset:57344
	s_waitcnt vmcnt(4) lgkmcnt(1)
	v_mfma_f32_32x32x16_bf16 v[80:95], v[2:5], v[160:163], v[80:95]
	s_waitcnt lgkmcnt(0)
	v_mfma_f32_32x32x16_bf16 v[96:111], v[6:9], v[160:163], v[96:111]
	ds_read_b128 v[2:5], v10 offset:49280
	ds_read_b128 v[6:9], v10 offset:57472
	s_waitcnt vmcnt(3) lgkmcnt(1)
	v_mfma_f32_32x32x16_bf16 v[80:95], v[2:5], v[156:159], v[80:95]
	s_waitcnt lgkmcnt(0)
	v_mfma_f32_32x32x16_bf16 v[96:111], v[6:9], v[156:159], v[96:111]
	ds_read_b128 v[2:5], v11 offset:49280
	ds_read_b128 v[6:9], v11 offset:57472
	s_waitcnt vmcnt(2) lgkmcnt(1)
	v_mfma_f32_32x32x16_bf16 v[80:95], v[2:5], v[152:155], v[80:95]
	s_waitcnt lgkmcnt(0)
	v_mfma_f32_32x32x16_bf16 v[96:111], v[6:9], v[152:155], v[96:111]
	ds_read_b128 v[2:5], v12 offset:49280
	ds_read_b128 v[6:9], v12 offset:57472
	s_waitcnt vmcnt(1) lgkmcnt(1)
	v_mfma_f32_32x32x16_bf16 v[80:95], v[2:5], v[148:151], v[80:95]
	s_waitcnt lgkmcnt(0)
	v_mfma_f32_32x32x16_bf16 v[96:111], v[6:9], v[148:151], v[96:111]
	ds_read_b128 v[2:5], v1 offset:49280
	ds_read_b128 v[6:9], v1 offset:57472
	s_waitcnt vmcnt(0) lgkmcnt(1)
	v_mfma_f32_32x32x16_bf16 v[80:95], v[2:5], v[144:147], v[80:95]
	s_waitcnt lgkmcnt(0)
	v_mfma_f32_32x32x16_bf16 v[96:111], v[6:9], v[144:147], v[96:111]
	s_branch .LBB0_274
.LBB0_273:
	s_setprio 0
	v_mov_b32_e32 v14, v0
	v_mov_b32_e32 v15, v0
	v_mov_b32_e32 v1, v0
	v_mov_b32_e32 v2, v0
	v_mov_b32_e32 v3, v0
	v_mov_b32_e32 v4, v0
	v_mov_b32_e32 v5, v0
	v_mov_b32_e32 v6, v0
	v_mov_b32_e32 v7, v0
	v_mov_b32_e32 v8, v0
	v_mov_b32_e32 v9, v0
	v_mov_b32_e32 v10, v0
	v_mov_b32_e32 v11, v0
	v_mov_b32_e32 v12, v0
	v_mov_b32_e32 v13, v0
	v_mov_b64_e32 v[94:95], v[14:15]
	v_mov_b64_e32 v[110:111], v[14:15]
	v_mov_b64_e32 v[92:93], v[12:13]
	v_mov_b64_e32 v[90:91], v[10:11]
	v_mov_b64_e32 v[88:89], v[8:9]
	v_mov_b64_e32 v[86:87], v[6:7]
	v_mov_b64_e32 v[84:85], v[4:5]
	v_mov_b64_e32 v[82:83], v[2:3]
	v_mov_b64_e32 v[80:81], v[0:1]
	v_mov_b64_e32 v[108:109], v[12:13]
	v_mov_b64_e32 v[106:107], v[10:11]
	v_mov_b64_e32 v[104:105], v[8:9]
	v_mov_b64_e32 v[102:103], v[6:7]
	v_mov_b64_e32 v[100:101], v[4:5]
	v_mov_b64_e32 v[98:99], v[2:3]
	v_mov_b64_e32 v[96:97], v[0:1]

; __global__ void __launch_bounds__(NWAVES * 64, 2) fwd_kernel(Args args_) {
;     ...
;                 }
;             }
;     ...
;         } break;
.LBB0_420:
	s_setprio 0
	s_mov_b64 s[0:1], 0
